# attention tile body hand-rescheduled: S0/S1 in separate accumulators, exp2/pack in place, softmax VALU interleaved with MFMAs, LDS-DMA issued between MFMAs
# speedup vs baseline: 1.0204x; 1.0204x over previous
.LBB0_531:
	s_add_i32 s10, s33, 2
	s_cmp_ge_u32 s10, s28
	s_cselect_b64 s[22:23], -1, 0
	s_mov_b64 s[34:35], -1
	s_cmp_gt_i32 s33, s21
	s_cbranch_scc1 .Lat1_skip
	s_and_b64 vcc, exec, s[22:23]
	s_cbranch_vccnz .Lat1_nodma
	v_mov_b32_e32 v206, v217
	s_mul_i32 s10, s0, 0xa000
	v_lshlrev_b32_e32 v209, 3, v206
	v_lshrrev_b32_e32 v207, 1, v206
	v_lshlrev_b32_e32 v208, 7, v206
	v_and_b32_e32 v209, 8, v209
	v_ashrrev_i32_e32 v206, 5, v206
	v_add_u32_e32 v206, v209, v206
	v_and_b32_e32 v208, 0xf00, v208
	v_bitop3_b32 v209, v206, v207, 7 bitop3:0x78
	v_add_u32_e32 v210, 2, v206
	v_add_u32_e32 v211, 4, v206
	v_add_u32_e32 v206, 6, v206
	v_add_u32_e32 v208, s10, v208
	v_bitop3_b32 v210, v210, v207, 7 bitop3:0x78
	v_bitop3_b32 v211, v211, v207, 7 bitop3:0x78
	v_bitop3_b32 v206, v206, v207, 7 bitop3:0x78
	v_lshl_add_u32 v14, v209, 4, v208
	v_lshl_add_u32 v15, v210, 4, v208
	v_lshl_add_u32 v176, v211, 4, v208
	v_lshl_add_u32 v177, v206, 4, v208
	ds_read_b128 v[144:147], v14 offset:0
	ds_read_b128 v[148:151], v15 offset:0
	ds_read_b128 v[152:155], v176 offset:0
	ds_read_b128 v[156:159], v177 offset:0
	ds_read_b128 v[160:163], v14 offset:8192
	ds_read_b128 v[164:167], v15 offset:8192
	ds_read_b128 v[168:171], v176 offset:8192
	ds_read_b128 v[172:175], v177 offset:8192
	ds_read_b128 v[2:5], v14 offset:16384
	ds_read_b128 v[6:9], v15 offset:16384
	ds_read_b128 v[10:13], v176 offset:16384
	ds_read_b128 v[238:241], v177 offset:16384
	v_mad_u64_u32 v[202:203], s[10:11], s86, v228, v[180:181]
	s_mul_i32 s10, s7, 0xa000
	s_add_i32 s10, s9, s10
	s_mov_b32 m0, s10
	v_lshl_add_u64 v[204:205], v[202:203], 0, s[94:95]
	global_load_lds_dwordx4 v[202:203], off
	s_add_i32 m0, s10, 0x2000
	v_lshl_add_u64 v[202:203], v[202:203], 0, s[96:97]
	global_load_lds_dwordx4 v[204:205], off
	s_waitcnt lgkmcnt(8)
	v_mfma_f32_32x32x16_bf16 v[80:95], v[144:147], v[132:135], 0
	s_add_i32 m0, s10, 0x4000
	v_mfma_f32_32x32x16_bf16 v[80:95], v[148:151], v[128:131], v[80:95]
	global_load_lds_dwordx4 v[202:203], off
	v_lshl_add_u64 v[202:203], s[86:87], 1, v[182:183]
	s_add_i32 m0, s10, 0x6000
	v_mfma_f32_32x32x16_bf16 v[80:95], v[152:155], v[124:127], v[80:95]
	global_load_lds_dwordx4 v[202:203], off
	v_lshl_add_u64 v[202:203], v[202:203], 0, s[92:93]
	s_add_i32 m0, s10, 0x8000
	v_mfma_f32_32x32x16_bf16 v[80:95], v[156:159], v[120:123], v[80:95]
	global_load_lds_dwordx4 v[202:203], off
	ds_read_b128 v[144:147], v14 offset:4096
	ds_read_b128 v[148:151], v15 offset:4096
	ds_read_b128 v[152:155], v176 offset:4096
	ds_read_b128 v[156:159], v177 offset:4096
	s_waitcnt lgkmcnt(8)
	v_mfma_f32_32x32x16_bf16 v[80:95], v[160:163], v[116:119], v[80:95]
	v_mfma_f32_32x32x16_bf16 v[80:95], v[164:167], v[112:115], v[80:95]
	v_mfma_f32_32x32x16_bf16 v[80:95], v[168:171], v[108:111], v[80:95]
	v_mfma_f32_32x32x16_bf16 v[80:95], v[172:175], v[104:107], v[80:95]
	ds_read_b128 v[160:163], v14 offset:12288
	ds_read_b128 v[164:167], v15 offset:12288
	ds_read_b128 v[168:171], v176 offset:12288
	ds_read_b128 v[172:175], v177 offset:12288
	s_waitcnt lgkmcnt(8)
	v_mfma_f32_32x32x16_bf16 v[80:95], v[2:5], v[100:103], v[80:95]
	v_mfma_f32_32x32x16_bf16 v[80:95], v[6:9], v[140:143], v[80:95]
	v_mfma_f32_32x32x16_bf16 v[80:95], v[10:13], v[96:99], v[80:95]
	v_mfma_f32_32x32x16_bf16 v[80:95], v[238:241], v[136:139], v[80:95]
	ds_read_b128 v[2:5], v14 offset:20480
	ds_read_b128 v[6:9], v15 offset:20480
	ds_read_b128 v[10:13], v176 offset:20480
	ds_read_b128 v[238:241], v177 offset:20480
	s_waitcnt lgkmcnt(8)
	v_mfma_f32_32x32x16_bf16 v[184:199], v[144:147], v[132:135], 0
	v_mfma_f32_32x32x16_bf16 v[184:199], v[148:151], v[128:131], v[184:199]
	v_mfma_f32_32x32x16_bf16 v[184:199], v[152:155], v[124:127], v[184:199]
	v_mfma_f32_32x32x16_bf16 v[184:199], v[156:159], v[120:123], v[184:199]
	ds_read_b128 v[144:147], v14 offset:24576
	ds_read_b128 v[148:151], v14 offset:28672
	ds_read_b128 v[152:155], v14 offset:32768
	ds_read_b128 v[156:159], v14 offset:36864
	s_waitcnt lgkmcnt(8)
	v_mfma_f32_32x32x16_bf16 v[184:199], v[160:163], v[116:119], v[184:199]
	v_med3_f32 v80, v80, s4, v236
	v_exp_f32_e32 v80, v80
	v_med3_f32 v81, v81, s4, v236
	v_exp_f32_e32 v81, v81
	v_mfma_f32_32x32x16_bf16 v[184:199], v[164:167], v[112:115], v[184:199]
	v_med3_f32 v82, v82, s4, v236
	v_exp_f32_e32 v82, v82
	v_med3_f32 v83, v83, s4, v236
	v_exp_f32_e32 v83, v83
	v_mfma_f32_32x32x16_bf16 v[184:199], v[168:171], v[108:111], v[184:199]
	v_med3_f32 v84, v84, s4, v236
	v_exp_f32_e32 v84, v84
	v_med3_f32 v85, v85, s4, v236
	v_exp_f32_e32 v85, v85
	v_mfma_f32_32x32x16_bf16 v[184:199], v[172:175], v[104:107], v[184:199]
	v_med3_f32 v86, v86, s4, v236
	v_exp_f32_e32 v86, v86
	v_med3_f32 v87, v87, s4, v236
	v_exp_f32_e32 v87, v87
	ds_read_b128 v[160:163], v15 offset:24576
	ds_read_b128 v[164:167], v15 offset:28672
	ds_read_b128 v[168:171], v15 offset:32768
	ds_read_b128 v[172:175], v15 offset:36864
	s_waitcnt lgkmcnt(8)
	v_mfma_f32_32x32x16_bf16 v[184:199], v[2:5], v[100:103], v[184:199]
	v_med3_f32 v88, v88, s4, v236
	v_exp_f32_e32 v88, v88
	v_med3_f32 v89, v89, s4, v236
	v_exp_f32_e32 v89, v89
	v_add_f32_e32 v200, v80, v81
	v_add_f32_e32 v200, v200, v82
	v_mfma_f32_32x32x16_bf16 v[184:199], v[6:9], v[140:143], v[184:199]
	v_med3_f32 v90, v90, s4, v236
	v_exp_f32_e32 v90, v90
	v_med3_f32 v91, v91, s4, v236
	v_exp_f32_e32 v91, v91
	v_add_f32_e32 v200, v200, v83
	v_add_f32_e32 v200, v200, v84
	v_mfma_f32_32x32x16_bf16 v[184:199], v[10:13], v[96:99], v[184:199]
	v_med3_f32 v92, v92, s4, v236
	v_exp_f32_e32 v92, v92
	v_med3_f32 v93, v93, s4, v236
	v_exp_f32_e32 v93, v93
	v_add_f32_e32 v200, v200, v85
	v_add_f32_e32 v200, v200, v86
	v_mfma_f32_32x32x16_bf16 v[184:199], v[238:241], v[136:139], v[184:199]
	v_med3_f32 v94, v94, s4, v236
	v_exp_f32_e32 v94, v94
	v_med3_f32 v95, v95, s4, v236
	v_exp_f32_e32 v95, v95
	v_add_f32_e32 v200, v200, v87
	ds_read_b128 v[2:5], v176 offset:24576
	ds_read_b128 v[6:9], v176 offset:28672
	ds_read_b128 v[10:13], v176 offset:32768
	ds_read_b128 v[238:241], v176 offset:36864
	v_cvt_pk_bf16_f32 v80, v80, v81
	v_cvt_pk_bf16_f32 v81, v82, v83
	v_cvt_pk_bf16_f32 v82, v84, v85
	v_cvt_pk_bf16_f32 v83, v86, v87
	v_add_f32_e32 v200, v200, v88
	v_add_f32_e32 v200, v200, v89
	s_waitcnt lgkmcnt(8)
	v_mfma_f32_32x32x16_bf16 v[64:79], v[80:83], v[144:147], v[64:79]
	v_med3_f32 v184, v184, s4, v236
	v_exp_f32_e32 v184, v184
	v_med3_f32 v185, v185, s4, v236
	v_exp_f32_e32 v185, v185
	v_add_f32_e32 v200, v200, v90
	v_add_f32_e32 v200, v200, v91
	v_mfma_f32_32x32x16_bf16 v[48:63], v[80:83], v[148:151], v[48:63]
	v_med3_f32 v186, v186, s4, v236
	v_exp_f32_e32 v186, v186
	v_med3_f32 v187, v187, s4, v236
	v_exp_f32_e32 v187, v187
	v_add_f32_e32 v200, v200, v92
	v_add_f32_e32 v200, v200, v93
	v_mfma_f32_32x32x16_bf16 v[32:47], v[80:83], v[152:155], v[32:47]
	v_med3_f32 v188, v188, s4, v236
	v_exp_f32_e32 v188, v188
	v_med3_f32 v189, v189, s4, v236
	v_exp_f32_e32 v189, v189
	v_add_f32_e32 v200, v200, v94
	v_add_f32_e32 v200, v200, v95
	v_mfma_f32_32x32x16_bf16 v[16:31], v[80:83], v[156:159], v[16:31]
	v_med3_f32 v190, v190, s4, v236
	v_exp_f32_e32 v190, v190
	v_med3_f32 v191, v191, s4, v236
	v_exp_f32_e32 v191, v191
	v_cvt_pk_bf16_f32 v84, v88, v89
	v_cvt_pk_bf16_f32 v85, v90, v91
	v_cvt_pk_bf16_f32 v86, v92, v93
	v_cvt_pk_bf16_f32 v87, v94, v95
	ds_read_b128 v[144:147], v177 offset:24576
	ds_read_b128 v[148:151], v177 offset:28672
	ds_read_b128 v[152:155], v177 offset:32768
	ds_read_b128 v[156:159], v177 offset:36864
	s_waitcnt lgkmcnt(8)
	v_mfma_f32_32x32x16_bf16 v[64:79], v[84:87], v[160:163], v[64:79]
	v_med3_f32 v192, v192, s4, v236
	v_exp_f32_e32 v192, v192
	v_med3_f32 v193, v193, s4, v236
	v_exp_f32_e32 v193, v193
	v_add_f32_e32 v201, v184, v185
	v_add_f32_e32 v201, v201, v186
	v_mfma_f32_32x32x16_bf16 v[48:63], v[84:87], v[164:167], v[48:63]
	v_med3_f32 v194, v194, s4, v236
	v_exp_f32_e32 v194, v194
	v_med3_f32 v195, v195, s4, v236
	v_exp_f32_e32 v195, v195
	v_add_f32_e32 v201, v201, v187
	v_add_f32_e32 v201, v201, v188
	v_mfma_f32_32x32x16_bf16 v[32:47], v[84:87], v[168:171], v[32:47]
	v_med3_f32 v196, v196, s4, v236
	v_exp_f32_e32 v196, v196
	v_med3_f32 v197, v197, s4, v236
	v_exp_f32_e32 v197, v197
	v_add_f32_e32 v201, v201, v189
	v_mfma_f32_32x32x16_bf16 v[16:31], v[84:87], v[172:175], v[16:31]
	v_med3_f32 v198, v198, s4, v236
	v_exp_f32_e32 v198, v198
	v_med3_f32 v199, v199, s4, v236
	v_exp_f32_e32 v199, v199
	v_add_f32_e32 v201, v201, v190
	v_cvt_pk_bf16_f32 v184, v184, v185
	v_cvt_pk_bf16_f32 v185, v186, v187
	v_cvt_pk_bf16_f32 v186, v188, v189
	v_cvt_pk_bf16_f32 v187, v190, v191
	v_add_f32_e32 v201, v201, v191
	s_waitcnt lgkmcnt(4)
	v_mfma_f32_32x32x16_bf16 v[64:79], v[184:187], v[2:5], v[64:79]
	v_add_f32_e32 v201, v201, v192
	v_add_f32_e32 v201, v201, v193
	v_add_f32_e32 v201, v201, v194
	v_mfma_f32_32x32x16_bf16 v[48:63], v[184:187], v[6:9], v[48:63]
	v_add_f32_e32 v201, v201, v195
	v_add_f32_e32 v201, v201, v196
	v_add_f32_e32 v201, v201, v197
	v_mfma_f32_32x32x16_bf16 v[32:47], v[184:187], v[10:13], v[32:47]
	v_add_f32_e32 v201, v201, v198
	v_add_f32_e32 v201, v201, v199
	v_cvt_pk_bf16_f32 v188, v192, v193
	v_cvt_pk_bf16_f32 v189, v194, v195
	v_cvt_pk_bf16_f32 v190, v196, v197
	v_cvt_pk_bf16_f32 v191, v198, v199
	v_mfma_f32_32x32x16_bf16 v[16:31], v[184:187], v[238:241], v[16:31]
	v_add_f32_e32 v200, v200, v201
	v_add_f32_e32 v218, v218, v200
	s_waitcnt lgkmcnt(0)
	v_mfma_f32_32x32x16_bf16 v[64:79], v[188:191], v[144:147], v[64:79]
	v_mfma_f32_32x32x16_bf16 v[48:63], v[188:191], v[148:151], v[48:63]
	v_mfma_f32_32x32x16_bf16 v[32:47], v[188:191], v[152:155], v[32:47]
	v_mfma_f32_32x32x16_bf16 v[16:31], v[188:191], v[156:159], v[16:31]
	s_waitcnt vmcnt(5) lgkmcnt(0)
	s_branch .LBB0_530
.Lat1_nodma:
	v_mov_b32_e32 v206, v217
	s_mul_i32 s10, s0, 0xa000
	v_lshlrev_b32_e32 v209, 3, v206
	v_lshrrev_b32_e32 v207, 1, v206
	v_lshlrev_b32_e32 v208, 7, v206
	v_and_b32_e32 v209, 8, v209
	v_ashrrev_i32_e32 v206, 5, v206
	v_add_u32_e32 v206, v209, v206
	v_and_b32_e32 v208, 0xf00, v208
	v_bitop3_b32 v209, v206, v207, 7 bitop3:0x78
	v_add_u32_e32 v210, 2, v206
	v_add_u32_e32 v211, 4, v206
	v_add_u32_e32 v206, 6, v206
	v_add_u32_e32 v208, s10, v208
	v_bitop3_b32 v210, v210, v207, 7 bitop3:0x78
	v_bitop3_b32 v211, v211, v207, 7 bitop3:0x78
	v_bitop3_b32 v206, v206, v207, 7 bitop3:0x78
	v_lshl_add_u32 v14, v209, 4, v208
	v_lshl_add_u32 v15, v210, 4, v208
	v_lshl_add_u32 v176, v211, 4, v208
	v_lshl_add_u32 v177, v206, 4, v208
	ds_read_b128 v[144:147], v14 offset:0
	ds_read_b128 v[148:151], v15 offset:0
	ds_read_b128 v[152:155], v176 offset:0
	ds_read_b128 v[156:159], v177 offset:0
	ds_read_b128 v[160:163], v14 offset:8192
	ds_read_b128 v[164:167], v15 offset:8192
	ds_read_b128 v[168:171], v176 offset:8192
	ds_read_b128 v[172:175], v177 offset:8192
	ds_read_b128 v[2:5], v14 offset:16384
	ds_read_b128 v[6:9], v15 offset:16384
	ds_read_b128 v[10:13], v176 offset:16384
	ds_read_b128 v[238:241], v177 offset:16384
	s_waitcnt lgkmcnt(8)
	v_mfma_f32_32x32x16_bf16 v[80:95], v[144:147], v[132:135], 0
	v_mfma_f32_32x32x16_bf16 v[80:95], v[148:151], v[128:131], v[80:95]
	v_mfma_f32_32x32x16_bf16 v[80:95], v[152:155], v[124:127], v[80:95]
	v_mfma_f32_32x32x16_bf16 v[80:95], v[156:159], v[120:123], v[80:95]
	ds_read_b128 v[144:147], v14 offset:4096
	ds_read_b128 v[148:151], v15 offset:4096
	ds_read_b128 v[152:155], v176 offset:4096
	ds_read_b128 v[156:159], v177 offset:4096
	s_waitcnt lgkmcnt(8)
	v_mfma_f32_32x32x16_bf16 v[80:95], v[160:163], v[116:119], v[80:95]
	v_mfma_f32_32x32x16_bf16 v[80:95], v[164:167], v[112:115], v[80:95]
	v_mfma_f32_32x32x16_bf16 v[80:95], v[168:171], v[108:111], v[80:95]
	v_mfma_f32_32x32x16_bf16 v[80:95], v[172:175], v[104:107], v[80:95]
	ds_read_b128 v[160:163], v14 offset:12288
	ds_read_b128 v[164:167], v15 offset:12288
	ds_read_b128 v[168:171], v176 offset:12288
	ds_read_b128 v[172:175], v177 offset:12288
	s_waitcnt lgkmcnt(8)
	v_mfma_f32_32x32x16_bf16 v[80:95], v[2:5], v[100:103], v[80:95]
	v_mfma_f32_32x32x16_bf16 v[80:95], v[6:9], v[140:143], v[80:95]
	v_mfma_f32_32x32x16_bf16 v[80:95], v[10:13], v[96:99], v[80:95]
	v_mfma_f32_32x32x16_bf16 v[80:95], v[238:241], v[136:139], v[80:95]
	ds_read_b128 v[2:5], v14 offset:20480
	ds_read_b128 v[6:9], v15 offset:20480
	ds_read_b128 v[10:13], v176 offset:20480
	ds_read_b128 v[238:241], v177 offset:20480
	s_waitcnt lgkmcnt(8)
	v_mfma_f32_32x32x16_bf16 v[184:199], v[144:147], v[132:135], 0
	v_mfma_f32_32x32x16_bf16 v[184:199], v[148:151], v[128:131], v[184:199]
	v_mfma_f32_32x32x16_bf16 v[184:199], v[152:155], v[124:127], v[184:199]
	v_mfma_f32_32x32x16_bf16 v[184:199], v[156:159], v[120:123], v[184:199]
	ds_read_b128 v[144:147], v14 offset:24576
	ds_read_b128 v[148:151], v14 offset:28672
	ds_read_b128 v[152:155], v14 offset:32768
	ds_read_b128 v[156:159], v14 offset:36864
	s_waitcnt lgkmcnt(8)
	v_mfma_f32_32x32x16_bf16 v[184:199], v[160:163], v[116:119], v[184:199]
	v_med3_f32 v80, v80, s4, v236
	v_exp_f32_e32 v80, v80
	v_med3_f32 v81, v81, s4, v236
	v_exp_f32_e32 v81, v81
	v_mfma_f32_32x32x16_bf16 v[184:199], v[164:167], v[112:115], v[184:199]
	v_med3_f32 v82, v82, s4, v236
	v_exp_f32_e32 v82, v82
	v_med3_f32 v83, v83, s4, v236
	v_exp_f32_e32 v83, v83
	v_mfma_f32_32x32x16_bf16 v[184:199], v[168:171], v[108:111], v[184:199]
	v_med3_f32 v84, v84, s4, v236
	v_exp_f32_e32 v84, v84
	v_med3_f32 v85, v85, s4, v236
	v_exp_f32_e32 v85, v85
	v_mfma_f32_32x32x16_bf16 v[184:199], v[172:175], v[104:107], v[184:199]
	v_med3_f32 v86, v86, s4, v236
	v_exp_f32_e32 v86, v86
	v_med3_f32 v87, v87, s4, v236
	v_exp_f32_e32 v87, v87
	ds_read_b128 v[160:163], v15 offset:24576
	ds_read_b128 v[164:167], v15 offset:28672
	ds_read_b128 v[168:171], v15 offset:32768
	ds_read_b128 v[172:175], v15 offset:36864
	s_waitcnt lgkmcnt(8)
	v_mfma_f32_32x32x16_bf16 v[184:199], v[2:5], v[100:103], v[184:199]
	v_med3_f32 v88, v88, s4, v236
	v_exp_f32_e32 v88, v88
	v_med3_f32 v89, v89, s4, v236
	v_exp_f32_e32 v89, v89
	v_add_f32_e32 v200, v80, v81
	v_add_f32_e32 v200, v200, v82
	v_mfma_f32_32x32x16_bf16 v[184:199], v[6:9], v[140:143], v[184:199]
	v_med3_f32 v90, v90, s4, v236
	v_exp_f32_e32 v90, v90
	v_med3_f32 v91, v91, s4, v236
	v_exp_f32_e32 v91, v91
	v_add_f32_e32 v200, v200, v83
	v_add_f32_e32 v200, v200, v84
	v_mfma_f32_32x32x16_bf16 v[184:199], v[10:13], v[96:99], v[184:199]
	v_med3_f32 v92, v92, s4, v236
	v_exp_f32_e32 v92, v92
	v_med3_f32 v93, v93, s4, v236
	v_exp_f32_e32 v93, v93
	v_add_f32_e32 v200, v200, v85
	v_add_f32_e32 v200, v200, v86
	v_mfma_f32_32x32x16_bf16 v[184:199], v[238:241], v[136:139], v[184:199]
	v_med3_f32 v94, v94, s4, v236
	v_exp_f32_e32 v94, v94
	v_med3_f32 v95, v95, s4, v236
	v_exp_f32_e32 v95, v95
	v_add_f32_e32 v200, v200, v87
	ds_read_b128 v[2:5], v176 offset:24576
	ds_read_b128 v[6:9], v176 offset:28672
	ds_read_b128 v[10:13], v176 offset:32768
	ds_read_b128 v[238:241], v176 offset:36864
	v_cvt_pk_bf16_f32 v80, v80, v81
	v_cvt_pk_bf16_f32 v81, v82, v83
	v_cvt_pk_bf16_f32 v82, v84, v85
	v_cvt_pk_bf16_f32 v83, v86, v87
	v_add_f32_e32 v200, v200, v88
	v_add_f32_e32 v200, v200, v89
	s_waitcnt lgkmcnt(8)
	v_mfma_f32_32x32x16_bf16 v[64:79], v[80:83], v[144:147], v[64:79]
	v_med3_f32 v184, v184, s4, v236
	v_exp_f32_e32 v184, v184
	v_med3_f32 v185, v185, s4, v236
	v_exp_f32_e32 v185, v185
	v_add_f32_e32 v200, v200, v90
	v_add_f32_e32 v200, v200, v91
	v_mfma_f32_32x32x16_bf16 v[48:63], v[80:83], v[148:151], v[48:63]
	v_med3_f32 v186, v186, s4, v236
	v_exp_f32_e32 v186, v186
	v_med3_f32 v187, v187, s4, v236
	v_exp_f32_e32 v187, v187
	v_add_f32_e32 v200, v200, v92
	v_add_f32_e32 v200, v200, v93
	v_mfma_f32_32x32x16_bf16 v[32:47], v[80:83], v[152:155], v[32:47]
	v_med3_f32 v188, v188, s4, v236
	v_exp_f32_e32 v188, v188
	v_med3_f32 v189, v189, s4, v236
	v_exp_f32_e32 v189, v189
	v_add_f32_e32 v200, v200, v94
	v_add_f32_e32 v200, v200, v95
	v_mfma_f32_32x32x16_bf16 v[16:31], v[80:83], v[156:159], v[16:31]
	v_med3_f32 v190, v190, s4, v236
	v_exp_f32_e32 v190, v190
	v_med3_f32 v191, v191, s4, v236
	v_exp_f32_e32 v191, v191
	v_cvt_pk_bf16_f32 v84, v88, v89
	v_cvt_pk_bf16_f32 v85, v90, v91
	v_cvt_pk_bf16_f32 v86, v92, v93
	v_cvt_pk_bf16_f32 v87, v94, v95
	ds_read_b128 v[144:147], v177 offset:24576
	ds_read_b128 v[148:151], v177 offset:28672
	ds_read_b128 v[152:155], v177 offset:32768
	ds_read_b128 v[156:159], v177 offset:36864
	s_waitcnt lgkmcnt(8)
	v_mfma_f32_32x32x16_bf16 v[64:79], v[84:87], v[160:163], v[64:79]
	v_med3_f32 v192, v192, s4, v236
	v_exp_f32_e32 v192, v192
	v_med3_f32 v193, v193, s4, v236
	v_exp_f32_e32 v193, v193
	v_add_f32_e32 v201, v184, v185
	v_add_f32_e32 v201, v201, v186
	v_mfma_f32_32x32x16_bf16 v[48:63], v[84:87], v[164:167], v[48:63]
	v_med3_f32 v194, v194, s4, v236
	v_exp_f32_e32 v194, v194
	v_med3_f32 v195, v195, s4, v236
	v_exp_f32_e32 v195, v195
	v_add_f32_e32 v201, v201, v187
	v_add_f32_e32 v201, v201, v188
	v_mfma_f32_32x32x16_bf16 v[32:47], v[84:87], v[168:171], v[32:47]
	v_med3_f32 v196, v196, s4, v236
	v_exp_f32_e32 v196, v196
	v_med3_f32 v197, v197, s4, v236
	v_exp_f32_e32 v197, v197
	v_add_f32_e32 v201, v201, v189
	v_mfma_f32_32x32x16_bf16 v[16:31], v[84:87], v[172:175], v[16:31]
	v_med3_f32 v198, v198, s4, v236
	v_exp_f32_e32 v198, v198
	v_med3_f32 v199, v199, s4, v236
	v_exp_f32_e32 v199, v199
	v_add_f32_e32 v201, v201, v190
	v_cvt_pk_bf16_f32 v184, v184, v185
	v_cvt_pk_bf16_f32 v185, v186, v187
	v_cvt_pk_bf16_f32 v186, v188, v189
	v_cvt_pk_bf16_f32 v187, v190, v191
	v_add_f32_e32 v201, v201, v191
	s_waitcnt lgkmcnt(4)
	v_mfma_f32_32x32x16_bf16 v[64:79], v[184:187], v[2:5], v[64:79]
	v_add_f32_e32 v201, v201, v192
	v_add_f32_e32 v201, v201, v193
	v_add_f32_e32 v201, v201, v194
	v_mfma_f32_32x32x16_bf16 v[48:63], v[184:187], v[6:9], v[48:63]
	v_add_f32_e32 v201, v201, v195
	v_add_f32_e32 v201, v201, v196
	v_add_f32_e32 v201, v201, v197
	v_mfma_f32_32x32x16_bf16 v[32:47], v[184:187], v[10:13], v[32:47]
	v_add_f32_e32 v201, v201, v198
	v_add_f32_e32 v201, v201, v199
	v_cvt_pk_bf16_f32 v188, v192, v193
	v_cvt_pk_bf16_f32 v189, v194, v195
	v_cvt_pk_bf16_f32 v190, v196, v197
	v_cvt_pk_bf16_f32 v191, v198, v199
	v_mfma_f32_32x32x16_bf16 v[16:31], v[184:187], v[238:241], v[16:31]
	v_add_f32_e32 v200, v200, v201
	v_add_f32_e32 v218, v218, v200
	s_waitcnt lgkmcnt(0)
	v_mfma_f32_32x32x16_bf16 v[64:79], v[188:191], v[144:147], v[64:79]
	v_mfma_f32_32x32x16_bf16 v[48:63], v[188:191], v[148:151], v[48:63]
	v_mfma_f32_32x32x16_bf16 v[32:47], v[188:191], v[152:155], v[32:47]
	v_mfma_f32_32x32x16_bf16 v[16:31], v[188:191], v[156:159], v[16:31]
	s_waitcnt vmcnt(0) lgkmcnt(0)
	s_branch .LBB0_530
.Lat1_skip:
	s_and_b64 vcc, exec, s[22:23]
	s_cbranch_vccnz .Lat1_skip_nodma
	v_mad_u64_u32 v[202:203], s[10:11], s86, v228, v[180:181]
	s_mul_i32 s10, s7, 0xa000
	s_add_i32 s10, s9, s10
	s_mov_b32 m0, s10
	v_lshl_add_u64 v[204:205], v[202:203], 0, s[94:95]
	global_load_lds_dwordx4 v[202:203], off
	s_add_i32 m0, s10, 0x2000
	v_lshl_add_u64 v[202:203], v[202:203], 0, s[96:97]
	global_load_lds_dwordx4 v[204:205], off
	s_add_i32 m0, s10, 0x4000
	s_nop 0
	global_load_lds_dwordx4 v[202:203], off
	v_lshl_add_u64 v[202:203], s[86:87], 1, v[182:183]
	s_add_i32 m0, s10, 0x6000
	s_nop 0
	global_load_lds_dwordx4 v[202:203], off
	v_lshl_add_u64 v[202:203], v[202:203], 0, s[92:93]
	s_add_i32 m0, s10, 0x8000
	s_nop 0
	global_load_lds_dwordx4 v[202:203], off
	s_waitcnt vmcnt(5) lgkmcnt(0)
	s_branch .LBB0_530
.Lat1_skip_nodma:
	s_waitcnt vmcnt(0) lgkmcnt(0)
	s_branch .LBB0_530

.LBB0_574:
	s_add_i32 s10, s33, 2
	s_cmp_ge_i32 s10, s21
	s_cselect_b64 s[22:23], -1, 0
	s_mov_b64 s[34:35], -1
	s_cmp_gt_i32 s33, s9
	s_cbranch_scc1 .Lat2_skip
	s_and_b64 vcc, exec, s[22:23]
	s_cbranch_vccnz .Lat2_nodma
	v_mov_b32_e32 v208, v222
	s_mul_i32 s10, s28, 0xa000
	v_lshlrev_b32_e32 v211, 3, v208
	v_lshrrev_b32_e32 v209, 1, v208
	v_lshlrev_b32_e32 v210, 7, v208
	v_and_b32_e32 v211, 8, v211
	v_ashrrev_i32_e32 v208, 5, v208
	v_add_u32_e32 v208, v211, v208
	v_and_b32_e32 v210, 0xf00, v210
	v_bitop3_b32 v211, v208, v209, 7 bitop3:0x78
	v_add_u32_e32 v212, 2, v208
	v_add_u32_e32 v213, 4, v208
	v_add_u32_e32 v208, 6, v208
	v_add_u32_e32 v210, s10, v210
	v_bitop3_b32 v212, v212, v209, 7 bitop3:0x78
	v_bitop3_b32 v213, v213, v209, 7 bitop3:0x78
	v_bitop3_b32 v208, v208, v209, 7 bitop3:0x78
	v_lshl_add_u32 v198, v211, 4, v210
	v_lshl_add_u32 v199, v212, 4, v210
	v_lshl_add_u32 v200, v213, 4, v210
	v_lshl_add_u32 v201, v208, 4, v210
	ds_read_b128 v[130:133], v198 offset:0
	ds_read_b128 v[134:137], v199 offset:0
	ds_read_b128 v[138:141], v200 offset:0
	ds_read_b128 v[142:145], v201 offset:0
	ds_read_b128 v[146:149], v198 offset:8192
	ds_read_b128 v[150:153], v199 offset:8192
	ds_read_b128 v[154:157], v200 offset:8192
	ds_read_b128 v[158:161], v201 offset:8192
	ds_read_b128 v[162:165], v198 offset:16384
	ds_read_b128 v[166:169], v199 offset:16384
	ds_read_b128 v[170:173], v200 offset:16384
	ds_read_b128 v[176:179], v201 offset:16384
	v_mad_u64_u32 v[204:205], s[10:11], s86, v228, v[174:175]
	s_mul_i32 s10, s7, 0xa000
	s_add_i32 s10, s0, s10
	s_mov_b32 m0, s10
	v_lshl_add_u64 v[206:207], v[204:205], 0, s[94:95]
	global_load_lds_dwordx4 v[204:205], off
	s_add_i32 m0, s10, 0x2000
	v_lshl_add_u64 v[204:205], v[204:205], 0, s[96:97]
	global_load_lds_dwordx4 v[206:207], off
	s_waitcnt lgkmcnt(8)
	v_mfma_f32_32x32x16_bf16 v[66:81], v[130:133], v[118:121], 0
	s_add_i32 m0, s10, 0x4000
	v_mfma_f32_32x32x16_bf16 v[66:81], v[134:137], v[114:117], v[66:81]
	global_load_lds_dwordx4 v[204:205], off
	v_lshl_add_u64 v[204:205], s[86:87], 1, v[180:181]
	s_add_i32 m0, s10, 0x6000
	v_mfma_f32_32x32x16_bf16 v[66:81], v[138:141], v[110:113], v[66:81]
	global_load_lds_dwordx4 v[204:205], off
	v_lshl_add_u64 v[204:205], v[204:205], 0, s[92:93]
	s_add_i32 m0, s10, 0x8000
	v_mfma_f32_32x32x16_bf16 v[66:81], v[142:145], v[106:109], v[66:81]
	global_load_lds_dwordx4 v[204:205], off
	ds_read_b128 v[130:133], v198 offset:4096
	ds_read_b128 v[134:137], v199 offset:4096
	ds_read_b128 v[138:141], v200 offset:4096
	ds_read_b128 v[142:145], v201 offset:4096
	s_waitcnt lgkmcnt(8)
	v_mfma_f32_32x32x16_bf16 v[66:81], v[146:149], v[102:105], v[66:81]
	v_mfma_f32_32x32x16_bf16 v[66:81], v[150:153], v[98:101], v[66:81]
	v_mfma_f32_32x32x16_bf16 v[66:81], v[154:157], v[94:97], v[66:81]
	v_mfma_f32_32x32x16_bf16 v[66:81], v[158:161], v[90:93], v[66:81]
	ds_read_b128 v[146:149], v198 offset:12288
	ds_read_b128 v[150:153], v199 offset:12288
	ds_read_b128 v[154:157], v200 offset:12288
	ds_read_b128 v[158:161], v201 offset:12288
	s_waitcnt lgkmcnt(8)
	v_mfma_f32_32x32x16_bf16 v[66:81], v[162:165], v[86:89], v[66:81]
	v_mfma_f32_32x32x16_bf16 v[66:81], v[166:169], v[126:129], v[66:81]
	v_mfma_f32_32x32x16_bf16 v[66:81], v[170:173], v[82:85], v[66:81]
	v_mfma_f32_32x32x16_bf16 v[66:81], v[176:179], v[122:125], v[66:81]
	ds_read_b128 v[162:165], v198 offset:20480
	ds_read_b128 v[166:169], v199 offset:20480
	ds_read_b128 v[170:173], v200 offset:20480
	ds_read_b128 v[176:179], v201 offset:20480
	s_waitcnt lgkmcnt(8)
	v_mfma_f32_32x32x16_bf16 v[182:197], v[130:133], v[118:121], 0
	v_mfma_f32_32x32x16_bf16 v[182:197], v[134:137], v[114:117], v[182:197]
	v_mfma_f32_32x32x16_bf16 v[182:197], v[138:141], v[110:113], v[182:197]
	v_mfma_f32_32x32x16_bf16 v[182:197], v[142:145], v[106:109], v[182:197]
	ds_read_b128 v[130:133], v198 offset:24576
	ds_read_b128 v[134:137], v198 offset:28672
	ds_read_b128 v[138:141], v198 offset:32768
	ds_read_b128 v[142:145], v198 offset:36864
	s_waitcnt lgkmcnt(8)
	v_mfma_f32_32x32x16_bf16 v[182:197], v[146:149], v[102:105], v[182:197]
	v_med3_f32 v66, v66, s4, v236
	v_exp_f32_e32 v66, v66
	v_med3_f32 v67, v67, s4, v236
	v_exp_f32_e32 v67, v67
	v_mfma_f32_32x32x16_bf16 v[182:197], v[150:153], v[98:101], v[182:197]
	v_med3_f32 v68, v68, s4, v236
	v_exp_f32_e32 v68, v68
	v_med3_f32 v69, v69, s4, v236
	v_exp_f32_e32 v69, v69
	v_mfma_f32_32x32x16_bf16 v[182:197], v[154:157], v[94:97], v[182:197]
	v_med3_f32 v70, v70, s4, v236
	v_exp_f32_e32 v70, v70
	v_med3_f32 v71, v71, s4, v236
	v_exp_f32_e32 v71, v71
	v_mfma_f32_32x32x16_bf16 v[182:197], v[158:161], v[90:93], v[182:197]
	v_med3_f32 v72, v72, s4, v236
	v_exp_f32_e32 v72, v72
	v_med3_f32 v73, v73, s4, v236
	v_exp_f32_e32 v73, v73
	ds_read_b128 v[146:149], v199 offset:24576
	ds_read_b128 v[150:153], v199 offset:28672
	ds_read_b128 v[154:157], v199 offset:32768
	ds_read_b128 v[158:161], v199 offset:36864
	s_waitcnt lgkmcnt(8)
	v_mfma_f32_32x32x16_bf16 v[182:197], v[162:165], v[86:89], v[182:197]
	v_med3_f32 v74, v74, s4, v236
	v_exp_f32_e32 v74, v74
	v_med3_f32 v75, v75, s4, v236
	v_exp_f32_e32 v75, v75
	v_add_f32_e32 v202, v66, v67
	v_add_f32_e32 v202, v202, v68
	v_mfma_f32_32x32x16_bf16 v[182:197], v[166:169], v[126:129], v[182:197]
	v_med3_f32 v76, v76, s4, v236
	v_exp_f32_e32 v76, v76
	v_med3_f32 v77, v77, s4, v236
	v_exp_f32_e32 v77, v77
	v_add_f32_e32 v202, v202, v69
	v_add_f32_e32 v202, v202, v70
	v_mfma_f32_32x32x16_bf16 v[182:197], v[170:173], v[82:85], v[182:197]
	v_med3_f32 v78, v78, s4, v236
	v_exp_f32_e32 v78, v78
	v_med3_f32 v79, v79, s4, v236
	v_exp_f32_e32 v79, v79
	v_add_f32_e32 v202, v202, v71
	v_add_f32_e32 v202, v202, v72
	v_mfma_f32_32x32x16_bf16 v[182:197], v[176:179], v[122:125], v[182:197]
	v_med3_f32 v80, v80, s4, v236
	v_exp_f32_e32 v80, v80
	v_med3_f32 v81, v81, s4, v236
	v_exp_f32_e32 v81, v81
	v_add_f32_e32 v202, v202, v73
	ds_read_b128 v[162:165], v200 offset:24576
	ds_read_b128 v[166:169], v200 offset:28672
	ds_read_b128 v[170:173], v200 offset:32768
	ds_read_b128 v[176:179], v200 offset:36864
	v_cvt_pk_bf16_f32 v66, v66, v67
	v_cvt_pk_bf16_f32 v67, v68, v69
	v_cvt_pk_bf16_f32 v68, v70, v71
	v_cvt_pk_bf16_f32 v69, v72, v73
	v_add_f32_e32 v202, v202, v74
	v_add_f32_e32 v202, v202, v75
	s_waitcnt lgkmcnt(8)
	v_mfma_f32_32x32x16_bf16 v[50:65], v[66:69], v[130:133], v[50:65]
	v_med3_f32 v182, v182, s4, v236
	v_exp_f32_e32 v182, v182
	v_med3_f32 v183, v183, s4, v236
	v_exp_f32_e32 v183, v183
	v_add_f32_e32 v202, v202, v76
	v_add_f32_e32 v202, v202, v77
	v_mfma_f32_32x32x16_bf16 v[34:49], v[66:69], v[134:137], v[34:49]
	v_med3_f32 v184, v184, s4, v236
	v_exp_f32_e32 v184, v184
	v_med3_f32 v185, v185, s4, v236
	v_exp_f32_e32 v185, v185
	v_add_f32_e32 v202, v202, v78
	v_add_f32_e32 v202, v202, v79
	v_mfma_f32_32x32x16_bf16 v[18:33], v[66:69], v[138:141], v[18:33]
	v_med3_f32 v186, v186, s4, v236
	v_exp_f32_e32 v186, v186
	v_med3_f32 v187, v187, s4, v236
	v_exp_f32_e32 v187, v187
	v_add_f32_e32 v202, v202, v80
	v_add_f32_e32 v202, v202, v81
	v_mfma_f32_32x32x16_bf16 v[2:17], v[66:69], v[142:145], v[2:17]
	v_med3_f32 v188, v188, s4, v236
	v_exp_f32_e32 v188, v188
	v_med3_f32 v189, v189, s4, v236
	v_exp_f32_e32 v189, v189
	v_cvt_pk_bf16_f32 v70, v74, v75
	v_cvt_pk_bf16_f32 v71, v76, v77
	v_cvt_pk_bf16_f32 v72, v78, v79
	v_cvt_pk_bf16_f32 v73, v80, v81
	ds_read_b128 v[130:133], v201 offset:24576
	ds_read_b128 v[134:137], v201 offset:28672
	ds_read_b128 v[138:141], v201 offset:32768
	ds_read_b128 v[142:145], v201 offset:36864
	s_waitcnt lgkmcnt(8)
	v_mfma_f32_32x32x16_bf16 v[50:65], v[70:73], v[146:149], v[50:65]
	v_med3_f32 v190, v190, s4, v236
	v_exp_f32_e32 v190, v190
	v_med3_f32 v191, v191, s4, v236
	v_exp_f32_e32 v191, v191
	v_add_f32_e32 v203, v182, v183
	v_add_f32_e32 v203, v203, v184
	v_mfma_f32_32x32x16_bf16 v[34:49], v[70:73], v[150:153], v[34:49]
	v_med3_f32 v192, v192, s4, v236
	v_exp_f32_e32 v192, v192
	v_med3_f32 v193, v193, s4, v236
	v_exp_f32_e32 v193, v193
	v_add_f32_e32 v203, v203, v185
	v_add_f32_e32 v203, v203, v186
	v_mfma_f32_32x32x16_bf16 v[18:33], v[70:73], v[154:157], v[18:33]
	v_med3_f32 v194, v194, s4, v236
	v_exp_f32_e32 v194, v194
	v_med3_f32 v195, v195, s4, v236
	v_exp_f32_e32 v195, v195
	v_add_f32_e32 v203, v203, v187
	v_mfma_f32_32x32x16_bf16 v[2:17], v[70:73], v[158:161], v[2:17]
	v_med3_f32 v196, v196, s4, v236
	v_exp_f32_e32 v196, v196
	v_med3_f32 v197, v197, s4, v236
	v_exp_f32_e32 v197, v197
	v_add_f32_e32 v203, v203, v188
	v_cvt_pk_bf16_f32 v182, v182, v183
	v_cvt_pk_bf16_f32 v183, v184, v185
	v_cvt_pk_bf16_f32 v184, v186, v187
	v_cvt_pk_bf16_f32 v185, v188, v189
	v_add_f32_e32 v203, v203, v189
	s_waitcnt lgkmcnt(4)
	v_mfma_f32_32x32x16_bf16 v[50:65], v[182:185], v[162:165], v[50:65]
	v_add_f32_e32 v203, v203, v190
	v_add_f32_e32 v203, v203, v191
	v_add_f32_e32 v203, v203, v192
	v_mfma_f32_32x32x16_bf16 v[34:49], v[182:185], v[166:169], v[34:49]
	v_add_f32_e32 v203, v203, v193
	v_add_f32_e32 v203, v203, v194
	v_add_f32_e32 v203, v203, v195
	v_mfma_f32_32x32x16_bf16 v[18:33], v[182:185], v[170:173], v[18:33]
	v_add_f32_e32 v203, v203, v196
	v_add_f32_e32 v203, v203, v197
	v_cvt_pk_bf16_f32 v186, v190, v191
	v_cvt_pk_bf16_f32 v187, v192, v193
	v_cvt_pk_bf16_f32 v188, v194, v195
	v_cvt_pk_bf16_f32 v189, v196, v197
	v_mfma_f32_32x32x16_bf16 v[2:17], v[182:185], v[176:179], v[2:17]
	v_add_f32_e32 v202, v202, v203
	v_add_f32_e32 v0, v0, v202
	s_waitcnt lgkmcnt(0)
	v_mfma_f32_32x32x16_bf16 v[50:65], v[186:189], v[130:133], v[50:65]
	v_mfma_f32_32x32x16_bf16 v[34:49], v[186:189], v[134:137], v[34:49]
	v_mfma_f32_32x32x16_bf16 v[18:33], v[186:189], v[138:141], v[18:33]
	v_mfma_f32_32x32x16_bf16 v[2:17], v[186:189], v[142:145], v[2:17]
	s_waitcnt vmcnt(5) lgkmcnt(0)
	s_branch .LBB0_573
.Lat2_nodma:
	v_mov_b32_e32 v208, v222
	s_mul_i32 s10, s28, 0xa000
	v_lshlrev_b32_e32 v211, 3, v208
	v_lshrrev_b32_e32 v209, 1, v208
	v_lshlrev_b32_e32 v210, 7, v208
	v_and_b32_e32 v211, 8, v211
	v_ashrrev_i32_e32 v208, 5, v208
	v_add_u32_e32 v208, v211, v208
	v_and_b32_e32 v210, 0xf00, v210
	v_bitop3_b32 v211, v208, v209, 7 bitop3:0x78
	v_add_u32_e32 v212, 2, v208
	v_add_u32_e32 v213, 4, v208
	v_add_u32_e32 v208, 6, v208
	v_add_u32_e32 v210, s10, v210
	v_bitop3_b32 v212, v212, v209, 7 bitop3:0x78
	v_bitop3_b32 v213, v213, v209, 7 bitop3:0x78
	v_bitop3_b32 v208, v208, v209, 7 bitop3:0x78
	v_lshl_add_u32 v198, v211, 4, v210
	v_lshl_add_u32 v199, v212, 4, v210
	v_lshl_add_u32 v200, v213, 4, v210
	v_lshl_add_u32 v201, v208, 4, v210
	ds_read_b128 v[130:133], v198 offset:0
	ds_read_b128 v[134:137], v199 offset:0
	ds_read_b128 v[138:141], v200 offset:0
	ds_read_b128 v[142:145], v201 offset:0
	ds_read_b128 v[146:149], v198 offset:8192
	ds_read_b128 v[150:153], v199 offset:8192
	ds_read_b128 v[154:157], v200 offset:8192
	ds_read_b128 v[158:161], v201 offset:8192
	ds_read_b128 v[162:165], v198 offset:16384
	ds_read_b128 v[166:169], v199 offset:16384
	ds_read_b128 v[170:173], v200 offset:16384
	ds_read_b128 v[176:179], v201 offset:16384
	s_waitcnt lgkmcnt(8)
	v_mfma_f32_32x32x16_bf16 v[66:81], v[130:133], v[118:121], 0
	v_mfma_f32_32x32x16_bf16 v[66:81], v[134:137], v[114:117], v[66:81]
	v_mfma_f32_32x32x16_bf16 v[66:81], v[138:141], v[110:113], v[66:81]
	v_mfma_f32_32x32x16_bf16 v[66:81], v[142:145], v[106:109], v[66:81]
	ds_read_b128 v[130:133], v198 offset:4096
	ds_read_b128 v[134:137], v199 offset:4096
	ds_read_b128 v[138:141], v200 offset:4096
	ds_read_b128 v[142:145], v201 offset:4096
	s_waitcnt lgkmcnt(8)
	v_mfma_f32_32x32x16_bf16 v[66:81], v[146:149], v[102:105], v[66:81]
	v_mfma_f32_32x32x16_bf16 v[66:81], v[150:153], v[98:101], v[66:81]
	v_mfma_f32_32x32x16_bf16 v[66:81], v[154:157], v[94:97], v[66:81]
	v_mfma_f32_32x32x16_bf16 v[66:81], v[158:161], v[90:93], v[66:81]
	ds_read_b128 v[146:149], v198 offset:12288
	ds_read_b128 v[150:153], v199 offset:12288
	ds_read_b128 v[154:157], v200 offset:12288
	ds_read_b128 v[158:161], v201 offset:12288
	s_waitcnt lgkmcnt(8)
	v_mfma_f32_32x32x16_bf16 v[66:81], v[162:165], v[86:89], v[66:81]
	v_mfma_f32_32x32x16_bf16 v[66:81], v[166:169], v[126:129], v[66:81]
	v_mfma_f32_32x32x16_bf16 v[66:81], v[170:173], v[82:85], v[66:81]
	v_mfma_f32_32x32x16_bf16 v[66:81], v[176:179], v[122:125], v[66:81]
	ds_read_b128 v[162:165], v198 offset:20480
	ds_read_b128 v[166:169], v199 offset:20480
	ds_read_b128 v[170:173], v200 offset:20480
	ds_read_b128 v[176:179], v201 offset:20480
	s_waitcnt lgkmcnt(8)
	v_mfma_f32_32x32x16_bf16 v[182:197], v[130:133], v[118:121], 0
	v_mfma_f32_32x32x16_bf16 v[182:197], v[134:137], v[114:117], v[182:197]
	v_mfma_f32_32x32x16_bf16 v[182:197], v[138:141], v[110:113], v[182:197]
	v_mfma_f32_32x32x16_bf16 v[182:197], v[142:145], v[106:109], v[182:197]
	ds_read_b128 v[130:133], v198 offset:24576
	ds_read_b128 v[134:137], v198 offset:28672
	ds_read_b128 v[138:141], v198 offset:32768
	ds_read_b128 v[142:145], v198 offset:36864
	s_waitcnt lgkmcnt(8)
	v_mfma_f32_32x32x16_bf16 v[182:197], v[146:149], v[102:105], v[182:197]
	v_med3_f32 v66, v66, s4, v236
	v_exp_f32_e32 v66, v66
	v_med3_f32 v67, v67, s4, v236
	v_exp_f32_e32 v67, v67
	v_mfma_f32_32x32x16_bf16 v[182:197], v[150:153], v[98:101], v[182:197]
	v_med3_f32 v68, v68, s4, v236
	v_exp_f32_e32 v68, v68
	v_med3_f32 v69, v69, s4, v236
	v_exp_f32_e32 v69, v69
	v_mfma_f32_32x32x16_bf16 v[182:197], v[154:157], v[94:97], v[182:197]
	v_med3_f32 v70, v70, s4, v236
	v_exp_f32_e32 v70, v70
	v_med3_f32 v71, v71, s4, v236
	v_exp_f32_e32 v71, v71
	v_mfma_f32_32x32x16_bf16 v[182:197], v[158:161], v[90:93], v[182:197]
	v_med3_f32 v72, v72, s4, v236
	v_exp_f32_e32 v72, v72
	v_med3_f32 v73, v73, s4, v236
	v_exp_f32_e32 v73, v73
	ds_read_b128 v[146:149], v199 offset:24576
	ds_read_b128 v[150:153], v199 offset:28672
	ds_read_b128 v[154:157], v199 offset:32768
	ds_read_b128 v[158:161], v199 offset:36864
	s_waitcnt lgkmcnt(8)
	v_mfma_f32_32x32x16_bf16 v[182:197], v[162:165], v[86:89], v[182:197]
	v_med3_f32 v74, v74, s4, v236
	v_exp_f32_e32 v74, v74
	v_med3_f32 v75, v75, s4, v236
	v_exp_f32_e32 v75, v75
	v_add_f32_e32 v202, v66, v67
	v_add_f32_e32 v202, v202, v68
	v_mfma_f32_32x32x16_bf16 v[182:197], v[166:169], v[126:129], v[182:197]
	v_med3_f32 v76, v76, s4, v236
	v_exp_f32_e32 v76, v76
	v_med3_f32 v77, v77, s4, v236
	v_exp_f32_e32 v77, v77
	v_add_f32_e32 v202, v202, v69
	v_add_f32_e32 v202, v202, v70
	v_mfma_f32_32x32x16_bf16 v[182:197], v[170:173], v[82:85], v[182:197]
	v_med3_f32 v78, v78, s4, v236
	v_exp_f32_e32 v78, v78
	v_med3_f32 v79, v79, s4, v236
	v_exp_f32_e32 v79, v79
	v_add_f32_e32 v202, v202, v71
	v_add_f32_e32 v202, v202, v72
	v_mfma_f32_32x32x16_bf16 v[182:197], v[176:179], v[122:125], v[182:197]
	v_med3_f32 v80, v80, s4, v236
	v_exp_f32_e32 v80, v80
	v_med3_f32 v81, v81, s4, v236
	v_exp_f32_e32 v81, v81
	v_add_f32_e32 v202, v202, v73
	ds_read_b128 v[162:165], v200 offset:24576
	ds_read_b128 v[166:169], v200 offset:28672
	ds_read_b128 v[170:173], v200 offset:32768
	ds_read_b128 v[176:179], v200 offset:36864
	v_cvt_pk_bf16_f32 v66, v66, v67
	v_cvt_pk_bf16_f32 v67, v68, v69
	v_cvt_pk_bf16_f32 v68, v70, v71
	v_cvt_pk_bf16_f32 v69, v72, v73
	v_add_f32_e32 v202, v202, v74
	v_add_f32_e32 v202, v202, v75
	s_waitcnt lgkmcnt(8)
	v_mfma_f32_32x32x16_bf16 v[50:65], v[66:69], v[130:133], v[50:65]
	v_med3_f32 v182, v182, s4, v236
	v_exp_f32_e32 v182, v182
	v_med3_f32 v183, v183, s4, v236
	v_exp_f32_e32 v183, v183
	v_add_f32_e32 v202, v202, v76
	v_add_f32_e32 v202, v202, v77
	v_mfma_f32_32x32x16_bf16 v[34:49], v[66:69], v[134:137], v[34:49]
	v_med3_f32 v184, v184, s4, v236
	v_exp_f32_e32 v184, v184
	v_med3_f32 v185, v185, s4, v236
	v_exp_f32_e32 v185, v185
	v_add_f32_e32 v202, v202, v78
	v_add_f32_e32 v202, v202, v79
	v_mfma_f32_32x32x16_bf16 v[18:33], v[66:69], v[138:141], v[18:33]
	v_med3_f32 v186, v186, s4, v236
	v_exp_f32_e32 v186, v186
	v_med3_f32 v187, v187, s4, v236
	v_exp_f32_e32 v187, v187
	v_add_f32_e32 v202, v202, v80
	v_add_f32_e32 v202, v202, v81
	v_mfma_f32_32x32x16_bf16 v[2:17], v[66:69], v[142:145], v[2:17]
	v_med3_f32 v188, v188, s4, v236
	v_exp_f32_e32 v188, v188
	v_med3_f32 v189, v189, s4, v236
	v_exp_f32_e32 v189, v189
	v_cvt_pk_bf16_f32 v70, v74, v75
	v_cvt_pk_bf16_f32 v71, v76, v77
	v_cvt_pk_bf16_f32 v72, v78, v79
	v_cvt_pk_bf16_f32 v73, v80, v81
	ds_read_b128 v[130:133], v201 offset:24576
	ds_read_b128 v[134:137], v201 offset:28672
	ds_read_b128 v[138:141], v201 offset:32768
	ds_read_b128 v[142:145], v201 offset:36864
	s_waitcnt lgkmcnt(8)
	v_mfma_f32_32x32x16_bf16 v[50:65], v[70:73], v[146:149], v[50:65]
	v_med3_f32 v190, v190, s4, v236
	v_exp_f32_e32 v190, v190
	v_med3_f32 v191, v191, s4, v236
	v_exp_f32_e32 v191, v191
	v_add_f32_e32 v203, v182, v183
	v_add_f32_e32 v203, v203, v184
	v_mfma_f32_32x32x16_bf16 v[34:49], v[70:73], v[150:153], v[34:49]
	v_med3_f32 v192, v192, s4, v236
	v_exp_f32_e32 v192, v192
	v_med3_f32 v193, v193, s4, v236
	v_exp_f32_e32 v193, v193
	v_add_f32_e32 v203, v203, v185
	v_add_f32_e32 v203, v203, v186
	v_mfma_f32_32x32x16_bf16 v[18:33], v[70:73], v[154:157], v[18:33]
	v_med3_f32 v194, v194, s4, v236
	v_exp_f32_e32 v194, v194
	v_med3_f32 v195, v195, s4, v236
	v_exp_f32_e32 v195, v195
	v_add_f32_e32 v203, v203, v187
	v_mfma_f32_32x32x16_bf16 v[2:17], v[70:73], v[158:161], v[2:17]
	v_med3_f32 v196, v196, s4, v236
	v_exp_f32_e32 v196, v196
	v_med3_f32 v197, v197, s4, v236
	v_exp_f32_e32 v197, v197
	v_add_f32_e32 v203, v203, v188
	v_cvt_pk_bf16_f32 v182, v182, v183
	v_cvt_pk_bf16_f32 v183, v184, v185
	v_cvt_pk_bf16_f32 v184, v186, v187
	v_cvt_pk_bf16_f32 v185, v188, v189
	v_add_f32_e32 v203, v203, v189
	s_waitcnt lgkmcnt(4)
	v_mfma_f32_32x32x16_bf16 v[50:65], v[182:185], v[162:165], v[50:65]
	v_add_f32_e32 v203, v203, v190
	v_add_f32_e32 v203, v203, v191
	v_add_f32_e32 v203, v203, v192
	v_mfma_f32_32x32x16_bf16 v[34:49], v[182:185], v[166:169], v[34:49]
	v_add_f32_e32 v203, v203, v193
	v_add_f32_e32 v203, v203, v194
	v_add_f32_e32 v203, v203, v195
	v_mfma_f32_32x32x16_bf16 v[18:33], v[182:185], v[170:173], v[18:33]
	v_add_f32_e32 v203, v203, v196
	v_add_f32_e32 v203, v203, v197
	v_cvt_pk_bf16_f32 v186, v190, v191
	v_cvt_pk_bf16_f32 v187, v192, v193
	v_cvt_pk_bf16_f32 v188, v194, v195
	v_cvt_pk_bf16_f32 v189, v196, v197
	v_mfma_f32_32x32x16_bf16 v[2:17], v[182:185], v[176:179], v[2:17]
	v_add_f32_e32 v202, v202, v203
	v_add_f32_e32 v0, v0, v202
	s_waitcnt lgkmcnt(0)
	v_mfma_f32_32x32x16_bf16 v[50:65], v[186:189], v[130:133], v[50:65]
	v_mfma_f32_32x32x16_bf16 v[34:49], v[186:189], v[134:137], v[34:49]
	v_mfma_f32_32x32x16_bf16 v[18:33], v[186:189], v[138:141], v[18:33]
	v_mfma_f32_32x32x16_bf16 v[2:17], v[186:189], v[142:145], v[2:17]
	s_waitcnt vmcnt(0) lgkmcnt(0)
	s_branch .LBB0_573
.Lat2_skip:
	s_and_b64 vcc, exec, s[22:23]
	s_cbranch_vccnz .Lat2_skip_nodma
	v_mad_u64_u32 v[204:205], s[10:11], s86, v228, v[174:175]
	s_mul_i32 s10, s7, 0xa000
	s_add_i32 s10, s0, s10
	s_mov_b32 m0, s10
	v_lshl_add_u64 v[206:207], v[204:205], 0, s[94:95]
	global_load_lds_dwordx4 v[204:205], off
	s_add_i32 m0, s10, 0x2000
	v_lshl_add_u64 v[204:205], v[204:205], 0, s[96:97]
	global_load_lds_dwordx4 v[206:207], off
	s_add_i32 m0, s10, 0x4000
	s_nop 0
	global_load_lds_dwordx4 v[204:205], off
	v_lshl_add_u64 v[204:205], s[86:87], 1, v[180:181]
	s_add_i32 m0, s10, 0x6000
	s_nop 0
	global_load_lds_dwordx4 v[204:205], off
	v_lshl_add_u64 v[204:205], v[204:205], 0, s[92:93]
	s_add_i32 m0, s10, 0x8000
	s_nop 0
	global_load_lds_dwordx4 v[204:205], off
	s_waitcnt vmcnt(5) lgkmcnt(0)
	s_branch .LBB0_573
